# v86 + GDN scan step: z prefetch loads issued after the output stores and the latch / first-half counted vmcnt waits corrected for the four younger operations (the step no longer drains the next chunk'
# speedup vs baseline: 1.0071x; 1.0033x over previous
; __device__ __forceinline__ void chain_load(ChainOps& o, const GdnP& P, int b, int h, int n, int w, int mt, int nh, int lane, int tid) {
;     const int l15 = lane & 15, quad = lane >> 4;
;     const int cn = b * 64 + n, unit = cn * 8 + h, row0 = cn * 64;
;     const bf16_t* wrow = P.wbuf + (size_t)unit * 8192 + (mt * 16 + l15) * 128 + quad * 8;
;     const bf16_t* qrow = P.proj + (size_t)(row0 + mt * 16 + l15) * NIN + C_GDN + h * 128 + quad * 8;
; #pragma unroll
;     for (int s = 0; s < 4; ++s) { o.wf[s] = *(const bf16x8*)(wrow + 32 * s); o.qf[s] = *(const bf16x8*)(qrow + 32 * s); }
;     const bf16_t* arow = P.attnb + (size_t)unit * 4096 + (mt * 16 + l15) * 64 + quad * 8;
;     const int kidx = w * 16 + l15;
;     const bf16_t* krow = P.proj + (size_t)(row0 + (kidx >> 1)) * NIN + C_GDN + 1024 + h * 128 + (kidx & 1) * 64 + quad * 8;
; #pragma unroll
;     for (int s = 0; s < 2; ++s) { o.af[s] = *(const bf16x8*)(arow + 32 * s); o.kf[s] = *(const bf16x8*)(krow + 32 * s); }
;     o.cd = P.cdb[unit];
;     const int cb = ((mt * 2 + nh) * 64 + lane) * 2;
;     const bf16_t* up = P.proj + (size_t)(row0 + (cb >> 4)) * NIN + C_GDN + 2048 + h * 128 + (cb & 15) * 8;
;     o.uf[0] = *(const u32x4*)up; o.uf[1] = *(const u32x4*)(up + 8);
; __device__ __forceinline__ void gdn_chain(LAS unsigned char* lds, const GdnP& P, const float* out_norm, int bh, const int tid) {
;     ...
;     for (int n = 0; n < 64; ++n) {
;         const int row0 = (b * 64 + n) * 64;
;         chain_load(nxt, P, b, h, n < 63 ? n + 1 : n, w, mt, nh, lane, tid);
;         f32x4 oacc[4];
; #pragma unroll
;         for (int q = 0; q < 4; ++q) { const int nt = 4 * nh + q; f32x4 a1 = (f32x4){0.f, 0.f, 0.f, 0.f}; oacc[q] = (f32x4){0.f, 0.f, 0.f, 0.f};
; #pragma unroll
;             for (int s = 0; s < 4; ++s) { const bf16x8 sf = *(const LAS bf16x8*)(lds + GC_ST + (nt * 16 + l15) * 272 + (quad * 8 + 32 * s) * 2);
;                 a1 = __builtin_amdgcn_mfma_f32_16x16x32_bf16(cur.wf[s], sf, a1, 0, 0, 0); oacc[q] = __builtin_amdgcn_mfma_f32_16x16x32_bf16(cur.qf[s], sf, oacc[q], 0, 0, 0); }
;             const unsigned u01 = cur.uf[q >> 1][(q & 1) * 2], u23 = cur.uf[q >> 1][(q & 1) * 2 + 1];
;             u32x2 pv; pv.x = pk2(bflo(u01) - a1[0], bfhi(u01) - a1[1]); pv.y = pk2(bflo(u23) - a1[2], bfhi(u23) - a1[3]);
;             *(LAS u32x2*)(lds + GC_VT + (nt * 16 + l15) * 144 + (mt * 16 + quad * 4) * 2) = pv; }
.LBB0_1125:
	s_or_b64 exec, exec, s[30:31]
	v_add_co_u32_e64 v84, s[30:31], s47, 1
	s_nop 0
	v_readfirstlane_b32 s47, v84
	s_waitcnt vmcnt(4)
	v_mov_b64_e32 v[84:85], v[88:89]
	v_add_u32_e32 v136, 64, v136
	s_andn2_b64 vcc, exec, s[30:31]
	v_mov_b64_e32 v[86:87], v[90:91]
	s_cbranch_vccz .LBB0_1120
.LBB0_1126:
	s_waitcnt vmcnt(14)
	v_mov_b64_e32 v[90:91], v[74:75]
	v_mov_b64_e32 v[88:89], v[72:73]
	ds_read_b128 v[72:75], v161
	ds_read_b128 v[92:95], v161 offset:64
	s_waitcnt vmcnt(13)
	v_mov_b64_e32 v[106:107], v[14:15]
	v_mov_b64_e32 v[104:105], v[12:13]
	s_waitcnt vmcnt(10)
	v_mov_b64_e32 v[110:111], v[22:23]
	s_waitcnt lgkmcnt(1)
	v_mfma_f32_16x16x32_bf16 v[96:99], v[88:91], v[72:75], 0
	s_waitcnt vmcnt(8)
	v_mov_b64_e32 v[102:103], v[30:31]
	v_mov_b64_e32 v[108:109], v[20:21]
	ds_read_b128 v[20:23], v161 offset:128
	v_mov_b64_e32 v[100:101], v[28:29]
	s_waitcnt lgkmcnt(1)
	v_mfma_f32_16x16x32_bf16 v[28:31], v[104:107], v[92:95], v[96:99]
	v_mov_b64_e32 v[180:181], v[18:19]
	v_mov_b64_e32 v[184:185], v[6:7]
	v_mov_b64_e32 v[178:179], v[16:17]
	v_mov_b64_e32 v[182:183], v[4:5]
	ds_read_b128 v[4:7], v161 offset:192
	s_waitcnt lgkmcnt(1)
	v_mfma_f32_16x16x32_bf16 v[16:19], v[108:111], v[20:23], v[28:31]
	v_mov_b64_e32 v[188:189], v[2:3]
	v_mov_b64_e32 v[186:187], v[0:1]
	s_waitcnt vmcnt(7)
	v_mov_b64_e32 v[192:193], v[10:11]
	v_mfma_f32_16x16x32_bf16 v[12:15], v[100:103], v[72:75], 0
	v_mov_b64_e32 v[190:191], v[8:9]
	s_waitcnt vmcnt(3)
	v_lshlrev_b32_e32 v8, 16, v80
	v_and_b32_e32 v9, 0xffff0000, v80
	s_waitcnt lgkmcnt(0)
	v_mfma_f32_16x16x32_bf16 v[0:3], v[178:181], v[4:7], v[16:19]
	s_add_i32 s0, s47, 0x41
	s_cmp_lg_u32 s47, -1
	s_cselect_b32 s0, s0, 63
	s_add_i32 s0, s0, s44
	s_lshl_b32 s30, s0, 3
	s_nop 2
	v_pk_add_f32 v[0:1], v[8:9], v[0:1] neg_lo:[0,1] neg_hi:[0,1]
	v_mfma_f32_16x16x32_bf16 v[8:11], v[182:185], v[92:95], v[12:15]
	v_cvt_pk_bf16_f32 v0, v0, v1
	s_or_b32 s30, s30, s43
	s_lshl_b32 s50, s0, 6
	v_lshlrev_b32_e32 v12, 16, v81
	v_and_b32_e32 v13, 0xffff0000, v81
	v_pk_add_f32 v[2:3], v[12:13], v[2:3] neg_lo:[0,1] neg_hi:[0,1]
	v_mfma_f32_16x16x32_bf16 v[8:11], v[186:189], v[20:23], v[8:11]
	v_cvt_pk_bf16_f32 v1, v2, v3
	v_add_u32_e32 v2, v155, v156
	ds_write_b64 v2, v[0:1] offset:34816
	ds_read_b128 v[0:3], v162
	v_mfma_f32_16x16x32_bf16 v[198:201], v[190:193], v[4:7], v[8:11]
	ds_read_b128 v[4:7], v162 offset:64
	ds_read_b128 v[12:15], v162 offset:128
	s_ashr_i32 s31, s30, 31
	s_waitcnt lgkmcnt(2)
	v_mfma_f32_16x16x32_bf16 v[8:11], v[88:91], v[0:3], 0
	v_mov_b64_e32 v[94:95], v[38:39]
	s_lshl_b64 s[48:49], s[30:31], 14
	v_or_b32_e32 v18, s50, v152
	v_mfma_f32_16x16x32_bf16 v[0:3], v[100:103], v[0:3], 0
	v_mov_b64_e32 v[202:203], s[16:17]
	v_mov_b64_e32 v[92:93], v[36:37]
	v_lshl_add_u64 v[16:17], v[132:133], 0, s[48:49]
	s_waitcnt lgkmcnt(1)
	v_mfma_f32_16x16x32_bf16 v[8:11], v[104:107], v[4:7], v[8:11]
	s_lshl_b32 s0, s45, 1
	v_mov_b64_e32 v[196:197], v[70:71]
	v_mov_b64_e32 v[194:195], v[68:69]
	v_mfma_f32_16x16x32_bf16 v[0:3], v[182:185], v[4:7], v[0:3]
	ds_read_b128 v[4:7], v162 offset:192
	v_mov_b64_e32 v[208:209], v[46:47]
	v_mov_b64_e32 v[98:99], v[50:51]
	s_waitcnt lgkmcnt(1)
	v_mfma_f32_16x16x32_bf16 v[8:11], v[108:111], v[12:15], v[8:11]
	v_mov_b64_e32 v[206:207], v[44:45]
	v_mov_b64_e32 v[96:97], v[48:49]
	v_add_u32_e32 v80, s50, v153
	s_waitcnt lgkmcnt(0)
	v_mfma_f32_16x16x32_bf16 v[8:11], v[178:181], v[4:7], v[8:11]
	v_mov_b32_e32 v138, v123
	v_mov_b32_e32 v123, v115
	v_mov_b32_e32 v127, v115
	v_mfma_f32_16x16x32_bf16 v[0:3], v[186:189], v[12:15], v[0:3]
	v_lshlrev_b32_e32 v14, 16, v82
	v_and_b32_e32 v15, 0xffff0000, v82
	s_nop 1
	v_pk_add_f32 v[8:9], v[14:15], v[8:9] neg_lo:[0,1] neg_hi:[0,1]
	v_lshlrev_b32_e32 v14, 16, v83
	v_and_b32_e32 v15, 0xffff0000, v83
	v_pk_add_f32 v[10:11], v[14:15], v[10:11] neg_lo:[0,1] neg_hi:[0,1]
	v_cvt_pk_bf16_f32 v8, v8, v9
	v_cvt_pk_bf16_f32 v9, v10, v11
	v_add_u32_e32 v10, v155, v157
	ds_write_b64 v10, v[8:9] offset:34816
	ds_read_b128 v[8:11], v163
	ds_read_b128 v[36:39], v163 offset:64
	v_mad_i64_i32 v[12:13], s[48:49], v18, s40, v[202:203]
	v_lshl_add_u64 v[12:13], v[12:13], 0, s[0:1]
	s_waitcnt lgkmcnt(1)
	v_mfma_f32_16x16x32_bf16 v[28:31], v[88:91], v[8:11], 0
	s_lshl_b64 s[48:49], s[30:31], 13
	v_lshl_add_u64 v[218:219], v[134:135], 0, s[48:49]
	v_mad_i64_i32 v[80:81], s[48:49], v80, s40, v[202:203]
	v_mfma_f32_16x16x32_bf16 v[210:213], v[190:193], v[4:7], v[0:3]
	s_lshl_b64 s[30:31], s[30:31], 2
	s_add_u32 s30, s2, s30
	s_addc_u32 s31, s3, s31
	v_lshl_add_u64 v[0:1], v[12:13], 0, v[114:115]
	v_add_co_u32_e32 v70, vcc, s41, v0
	v_lshl_add_u64 v[68:69], v[0:1], 0, s[22:23]
	s_nop 0
	v_addc_co_u32_e32 v71, vcc, 0, v1, vcc
	global_load_dwordx4 v[72:75], v[16:17], off
	global_load_dwordx4 v[12:15], v[16:17], off offset:64
	v_mfma_f32_16x16x32_bf16 v[44:47], v[100:103], v[8:11], 0
	global_load_dwordx4 v[4:7], v[68:69], off offset:64
	global_load_dwordx4 v[0:3], v[68:69], off offset:128
	global_load_dwordx4 v[20:23], v[16:17], off offset:128
	s_nop 0
	global_load_dwordx4 v[16:19], v[16:17], off offset:192
	v_pk_mul_f32 v[66:67], v[66:67], v[138:139] op_sel_hi:[1,0]
	v_pk_mul_f32 v[64:65], v[64:65], v[138:139] op_sel_hi:[1,0]
	s_waitcnt lgkmcnt(0)
; __device__ __forceinline__ void chain_load(ChainOps& o, const GdnP& P, int b, int h, int n, int w, int mt, int nh, int lane, int tid) {
;     ...
;     for (int s = 0; s < 4; ++s) { o.wf[s] = *(const bf16x8*)(wrow + 32 * s); o.qf[s] = *(const bf16x8*)(qrow + 32 * s); }
; __device__ __forceinline__ void gdn_chain(LAS unsigned char* lds, const GdnP& P, const float* out_norm, int bh, const int tid) {
;     ...
;         for (int q = 0; q < 4; ++q) { const int nt = 4 * nh + q; f32x4 a1 = (f32x4){0.f, 0.f, 0.f, 0.f}; oacc[q] = (f32x4){0.f, 0.f, 0.f, 0.f};
; #pragma unroll
;             for (int s = 0; s < 4; ++s) { const bf16x8 sf = *(const LAS bf16x8*)(lds + GC_ST + (nt * 16 + l15) * 272 + (quad * 8 + 32 * s) * 2);
;                 a1 = __builtin_amdgcn_mfma_f32_16x16x32_bf16(cur.wf[s], sf, a1, 0, 0, 0); oacc[q] = __builtin_amdgcn_mfma_f32_16x16x32_bf16(cur.qf[s], sf, oacc[q], 0, 0, 0); }
;             const unsigned u01 = cur.uf[q >> 1][(q & 1) * 2], u23 = cur.uf[q >> 1][(q & 1) * 2 + 1];
;             u32x2 pv; pv.x = pk2(bflo(u01) - a1[0], bfhi(u01) - a1[1]); pv.y = pk2(bflo(u23) - a1[2], bfhi(u23) - a1[3]);
;             *(LAS u32x2*)(lds + GC_VT + (nt * 16 + l15) * 144 + (mt * 16 + quad * 4) * 2) = pv; }
;         lds_barrier();
;         float ss[4] = {0.f, 0.f, 0.f, 0.f};
; #pragma unroll
;         for (int q = 0; q < 4; ++q) { const int nt = 4 * nh + q;
; #pragma unroll
;             for (int s = 0; s < 2; ++s) { const bf16x8 vf = *(const LAS bf16x8*)(lds + GC_VT + (nt * 16 + l15) * 144 + (quad * 8 + 32 * s) * 2); oacc[q] = __builtin_amdgcn_mfma_f32_16x16x32_bf16(cur.af[s], vf, oacc[q], 0, 0, 0); }
; #pragma unroll
;             for (int i = 0; i < 4; ++i) { ss[i] += oacc[q][i] * oacc[q][i]; *(LAS bf16_t*)(lds + GC_OB + (mt * 16 + quad * 4 + i) * 272 + (nt * 16 + l15) * 2) = (bf16_t)f2bf(oacc[q][i]); } }
; #pragma unroll
;         for (int nt = 0; nt < 8; ++nt) { sacc[nt] = sacc[nt] * cur.cd;
; #pragma unroll
;             for (int s = 0; s < 2; ++s) { const bf16x8 vf = *(const LAS bf16x8*)(lds + GC_VT + (nt * 16 + l15) * 144 + (quad * 8 + 32 * s) * 2); sacc[nt] = __builtin_amdgcn_mfma_f32_16x16x32_bf16(cur.kf[s], vf, sacc[nt], 0, 0, 0); }
;             u32x2 pv; pv.x = pk2(sacc[nt][0], sacc[nt][1]); pv.y = pk2(sacc[nt][2], sacc[nt][3]);
;             *(LAS u32x2*)(lds + GC_ST + (nt * 16 + l15) * 272 + (w * 16 + quad * 4) * 2) = pv; }
	v_mfma_f32_16x16x32_bf16 v[48:51], v[104:107], v[36:39], v[28:31]
	s_nop 2
	global_load_dwordx4 v[28:31], v[70:71], off offset:2048
	global_load_dwordx4 v[8:11], v[68:69], off offset:192
	ds_read_b128 v[68:71], v163 offset:128
	v_pk_mul_f32 v[62:63], v[62:63], v[138:139] op_sel_hi:[1,0]
	v_mfma_f32_16x16x32_bf16 v[36:39], v[182:185], v[36:39], v[44:47]
	v_mul_f32_e64 v60, v60, v138
	v_mul_f32_e64 v61, v61, v138
	v_pk_mul_f32 v[58:59], v[58:59], v[138:139] op_sel_hi:[1,0]
	v_pk_mul_f32 v[56:57], v[56:57], v[138:139] op_sel_hi:[1,0]
	ds_read_b128 v[44:47], v163 offset:192
	s_waitcnt lgkmcnt(1)
	v_mfma_f32_16x16x32_bf16 v[48:51], v[108:111], v[68:71], v[48:51]
	v_mul_f32_e64 v54, v54, v138
	v_mul_f32_e64 v55, v55, v138
	v_pk_mul_f32 v[52:53], v[52:53], v[138:139] op_sel_hi:[1,0]
	v_pk_mul_f32 v[42:43], v[42:43], v[138:139] op_sel_hi:[1,0]
	s_waitcnt lgkmcnt(0)
	v_mfma_f32_16x16x32_bf16 v[48:51], v[178:181], v[44:47], v[48:51]
	v_mul_f32_e64 v40, v40, v138
	v_mul_f32_e64 v41, v41, v138
	v_pk_mul_f32 v[34:35], v[34:35], v[138:139] op_sel_hi:[1,0]
	v_pk_mul_f32 v[32:33], v[32:33], v[138:139] op_sel_hi:[1,0]
	v_mfma_f32_16x16x32_bf16 v[36:39], v[186:189], v[68:71], v[36:39]
	s_waitcnt vmcnt(10)
	v_lshlrev_b32_e32 v70, 16, v84
	v_and_b32_e32 v71, 0xffff0000, v84
	v_pk_add_f32 v[48:49], v[70:71], v[48:49] neg_lo:[0,1] neg_hi:[0,1]
	v_lshlrev_b32_e32 v70, 16, v85
	v_and_b32_e32 v71, 0xffff0000, v85
	v_pk_add_f32 v[50:51], v[70:71], v[50:51] neg_lo:[0,1] neg_hi:[0,1]
	v_cvt_pk_bf16_f32 v48, v48, v49
	v_cvt_pk_bf16_f32 v49, v50, v51
	v_add_u32_e32 v50, v155, v158
	ds_write_b64 v50, v[48:49] offset:34816
	ds_read_b128 v[48:51], v164
	v_lshl_add_u64 v[68:69], v[80:81], 0, s[0:1]
	ds_read_b128 v[80:83], v164 offset:64
	v_lshl_add_u64 v[68:69], v[68:69], 0, v[122:123]
	s_waitcnt lgkmcnt(1)
	v_mfma_f32_16x16x32_bf16 v[88:91], v[88:91], v[48:51], 0
	v_add_u32_e32 v84, s50, v154
	v_pk_mul_f32 v[26:27], v[26:27], v[138:139] op_sel_hi:[1,0]
	v_pk_mul_f32 v[24:25], v[24:25], v[138:139] op_sel_hi:[1,0]
	v_mfma_f32_16x16x32_bf16 v[214:217], v[190:193], v[44:47], v[36:39]
	v_mul_f32_e64 v78, v78, v138
	v_mul_f32_e64 v79, v79, v138
	v_pk_mul_f32 v[76:77], v[76:77], v[138:139] op_sel_hi:[1,0]
	v_lshl_add_u64 v[36:37], v[68:69], 0, v[114:115]
	v_lshl_add_u64 v[38:39], v[36:37], 0, s[24:25]
	v_add_co_u32_e32 v36, vcc, s38, v36
	global_load_dwordx4 v[68:71], v[218:219], off
	global_load_dwordx4 v[44:47], v[218:219], off offset:64
	v_addc_co_u32_e32 v37, vcc, 0, v37, vcc
	v_mfma_f32_16x16x32_bf16 v[100:103], v[100:103], v[48:51], 0
	global_load_dwordx4 v[48:51], v[36:37], off
	s_nop 0
	global_load_dwordx4 v[36:39], v[38:39], off offset:64
	s_nop 0
	global_load_dword v123, v115, s[30:31]
	s_waitcnt lgkmcnt(0)
	v_mfma_f32_16x16x32_bf16 v[88:91], v[104:107], v[80:83], v[88:91]
	ds_read_b128 v[104:107], v164 offset:128
	v_mad_i64_i32 v[84:85], s[30:31], v84, s40, v[202:203]
	v_mfma_f32_16x16x32_bf16 v[80:83], v[182:185], v[80:83], v[100:103]
	v_lshl_add_u64 v[84:85], v[84:85], 0, s[0:1]
	s_nop 1
	ds_read_b128 v[100:103], v164 offset:192
	s_waitcnt lgkmcnt(1)
	v_mfma_f32_16x16x32_bf16 v[88:91], v[108:111], v[104:107], v[88:91]
	v_mfma_f32_16x16x32_bf16 v[104:107], v[186:189], v[104:107], v[80:83]
	s_nop 2
	v_lshl_add_u64 v[80:81], v[84:85], 0, v[126:127]
	s_waitcnt lgkmcnt(0)
	v_mfma_f32_16x16x32_bf16 v[108:111], v[178:181], v[100:103], v[88:91]
	v_lshl_add_u64 v[84:85], v[80:81], 0, s[26:27]
	v_add_co_u32_e32 v80, vcc, s38, v80
	v_mfma_f32_16x16x32_bf16 v[178:181], v[190:193], v[100:103], v[104:107]
	s_nop 0
	v_addc_co_u32_e32 v81, vcc, 0, v81, vcc
	global_load_dwordx4 v[80:83], v[80:81], off offset:2048
	s_nop 0
	global_load_dwordx4 v[88:91], v[84:85], off offset:16
	v_lshlrev_b32_e32 v84, 16, v86
	v_and_b32_e32 v85, 0xffff0000, v86
	v_lshlrev_b32_e32 v86, 16, v87
	v_and_b32_e32 v87, 0xffff0000, v87
	v_pk_add_f32 v[84:85], v[84:85], v[108:109] neg_lo:[0,1] neg_hi:[0,1]
	v_pk_add_f32 v[86:87], v[86:87], v[110:111] neg_lo:[0,1] neg_hi:[0,1]
	v_cvt_pk_bf16_f32 v84, v84, v85
	v_cvt_pk_bf16_f32 v85, v86, v87
	v_add_u32_e32 v86, v155, v159
	ds_write_b64 v86, v[84:85] offset:34816
	s_waitcnt lgkmcnt(0)
	s_barrier
	ds_read_b128 v[182:185], v148 offset:34816
	ds_read_b128 v[186:189], v148 offset:34880
	ds_read_b128 v[190:193], v148 offset:37120
	ds_read_b128 v[232:235], v148 offset:37184
	s_waitcnt lgkmcnt(2)
	v_mfma_f32_16x16x32_bf16 v[64:67], v[96:99], v[182:185], v[64:67]
	v_mfma_f32_16x16x32_bf16 v[64:67], v[92:95], v[186:189], v[64:67]
	s_cmp_lg_u32 s59, 0
	s_cbranch_scc1 .Lcb_skip0
	v_mfma_f32_16x16x32_bf16 v[84:87], v[194:197], v[182:185], v[198:201]
	v_mfma_f32_16x16x32_bf16 v[84:87], v[206:209], v[186:189], v[84:87]

; #define LAS __attribute__((address_space(3)))
; __device__ __forceinline__ unsigned pk2(float lo, float hi) { const f32x2 v = {lo, hi}; return __builtin_bit_cast(unsigned, __builtin_convertvector(v, hbf2)); }
; __device__ __forceinline__ unsigned f2bf(float f) { return pk2(f, 0.f) & 0xffffu; }
; __device__ __forceinline__ void lds_barrier() { asm volatile("s_waitcnt lgkmcnt(0)" ::: "memory"); __builtin_amdgcn_s_barrier(); asm volatile("" ::: "memory"); }
; __device__ __forceinline__ void gdn_chain(LAS unsigned char* lds, const GdnP& P, const float* out_norm, int bh, const int tid) {
;     ...
;             for (int i = 0; i < 4; ++i) { ss[i] += oacc[q][i] * oacc[q][i]; *(LAS bf16_t*)(lds + GC_OB + (mt * 16 + quad * 4 + i) * 272 + (nt * 16 + l15) * 2) = (bf16_t)f2bf(oacc[q][i]); } }
; #pragma unroll
;         for (int nt = 0; nt < 8; ++nt) { sacc[nt] = sacc[nt] * cur.cd;
; #pragma unroll
;             for (int s = 0; s < 2; ++s) { const bf16x8 vf = *(const LAS bf16x8*)(lds + GC_VT + (nt * 16 + l15) * 144 + (quad * 8 + 32 * s) * 2); sacc[nt] = __builtin_amdgcn_mfma_f32_16x16x32_bf16(cur.kf[s], vf, sacc[nt], 0, 0, 0); }
;             u32x2 pv; pv.x = pk2(sacc[nt][0], sacc[nt][1]); pv.y = pk2(sacc[nt][2], sacc[nt][3]);
;             *(LAS u32x2*)(lds + GC_ST + (nt * 16 + l15) * 272 + (w * 16 + quad * 4) * 2) = pv; }
; #pragma unroll
;         for (int i = 0; i < 4; ++i) { float s = ss[i]; s += __shfl_xor(s, 1); s += __shfl_xor(s, 2); s += __shfl_xor(s, 4); s += __shfl_xor(s, 8); if (l15 == 0) ((LAS float*)(lds + GC_RED))[(mt * 16 + quad * 4 + i) * 2 + nh] = s; }
;         lds_barrier();
.Lcb_skip7:
	v_cvt_pk_bf16_f32 v218, v24, v25
	v_cvt_pk_bf16_f32 v219, v26, v27
	ds_write_b64 v169, v[218:219] offset:26112
	s_nop 7
	v_cvt_pk_bf16_f32 v218, v76, v77
	v_cvt_pk_bf16_f32 v219, v78, v79
	ds_write_b64 v169, v[218:219] offset:30464
	v_cvt_pk_bf16_f32 v236, v84, s0
	v_cvt_pk_bf16_f32 v237, v85, s0
	v_cvt_pk_bf16_f32 v240, v86, s0
	v_cvt_pk_bf16_f32 v241, v87, s0
	ds_write_b16 v165, v236 offset:54272
	ds_write_b16 v165, v237 offset:54544
	ds_write_b16 v165, v240 offset:54816
	ds_write_b16 v165, v241 offset:55088
	v_cvt_pk_bf16_f32 v236, v100, s0
	v_cvt_pk_bf16_f32 v237, v101, s0
	v_cvt_pk_bf16_f32 v240, v102, s0
	v_cvt_pk_bf16_f32 v241, v103, s0
	ds_write_b16 v166, v236 offset:54272
	ds_write_b16 v166, v237 offset:54544
	ds_write_b16 v166, v240 offset:54816
	ds_write_b16 v166, v241 offset:55088
	v_cvt_pk_bf16_f32 v236, v104, s0
	v_cvt_pk_bf16_f32 v237, v105, s0
	v_cvt_pk_bf16_f32 v240, v106, s0
	v_cvt_pk_bf16_f32 v241, v107, s0
	ds_write_b16 v167, v236 offset:54272
	ds_write_b16 v167, v237 offset:54544
	ds_write_b16 v167, v240 offset:54816
	ds_write_b16 v167, v241 offset:55088
	v_cvt_pk_bf16_f32 v236, v108, s0
	v_cvt_pk_bf16_f32 v237, v109, s0
	v_cvt_pk_bf16_f32 v240, v110, s0
	v_cvt_pk_bf16_f32 v241, v111, s0
	ds_write_b16 v168, v236 offset:54272
	ds_write_b16 v168, v237 offset:54544
	ds_write_b16 v168, v240 offset:54816
	ds_write_b16 v168, v241 offset:55088
	v_mul_f32_e32 v96, v84, v84
	v_mul_f32_e32 v97, v85, v85
	v_mul_f32_e32 v98, v86, v86
	v_mul_f32_e32 v99, v87, v87
	v_fmac_f32_e32 v96, v100, v100
	v_fmac_f32_e32 v97, v101, v101
	v_fmac_f32_e32 v98, v102, v102
	v_fmac_f32_e32 v99, v103, v103
	v_fmac_f32_e32 v96, v104, v104
	v_fmac_f32_e32 v97, v105, v105
	v_fmac_f32_e32 v98, v106, v106
	v_fmac_f32_e32 v99, v107, v107
	v_fmac_f32_e32 v96, v108, v108
	v_fmac_f32_e32 v97, v109, v109
	v_fmac_f32_e32 v98, v110, v110
	v_fmac_f32_e32 v99, v111, v111
	v_add_f32_dpp v96, v96, v96 row_ror:8 row_mask:0xf bank_mask:0xf
	v_add_f32_dpp v97, v97, v97 row_ror:8 row_mask:0xf bank_mask:0xf
	v_add_f32_dpp v98, v98, v98 row_ror:8 row_mask:0xf bank_mask:0xf
	v_add_f32_dpp v99, v99, v99 row_ror:8 row_mask:0xf bank_mask:0xf
	v_add_f32_dpp v96, v96, v96 row_ror:4 row_mask:0xf bank_mask:0xf
	v_add_f32_dpp v97, v97, v97 row_ror:4 row_mask:0xf bank_mask:0xf
	v_add_f32_dpp v98, v98, v98 row_ror:4 row_mask:0xf bank_mask:0xf
	v_add_f32_dpp v99, v99, v99 row_ror:4 row_mask:0xf bank_mask:0xf
	v_add_f32_dpp v96, v96, v96 row_ror:2 row_mask:0xf bank_mask:0xf
	v_add_f32_dpp v97, v97, v97 row_ror:2 row_mask:0xf bank_mask:0xf
	v_add_f32_dpp v98, v98, v98 row_ror:2 row_mask:0xf bank_mask:0xf
	v_add_f32_dpp v99, v99, v99 row_ror:2 row_mask:0xf bank_mask:0xf
	v_add_f32_dpp v96, v96, v96 row_ror:1 row_mask:0xf bank_mask:0xf
	v_add_f32_dpp v97, v97, v97 row_ror:1 row_mask:0xf bank_mask:0xf
	v_add_f32_dpp v98, v98, v98 row_ror:1 row_mask:0xf bank_mask:0xf
	v_add_f32_dpp v99, v99, v99 row_ror:1 row_mask:0xf bank_mask:0xf
	s_and_saveexec_b64 s[30:31], s[6:7]
	v_add_u32_e32 v127, s46, v160
	ds_write_b32 v127, v96 offset:53248
	ds_write_b32 v170, v97 offset:53248
	ds_write_b32 v171, v98 offset:53248
	ds_write_b32 v172, v99 offset:53248
	s_or_b64 exec, exec, s[30:31]
	s_waitcnt lgkmcnt(0)
	v_mov_b64_e32 v[84:85], s[16:17]
	v_mad_i64_i32 v[84:85], s[30:31], v136, s40, v[84:85]
	s_waitcnt lgkmcnt(0)
	s_barrier
; #define LAS __attribute__((address_space(3)))
; __device__ __forceinline__ unsigned pk2(float lo, float hi) { const f32x2 v = {lo, hi}; return __builtin_bit_cast(unsigned, __builtin_convertvector(v, hbf2)); }
; __device__ __forceinline__ float sigmoidf_(float x) { return __builtin_amdgcn_rcpf(1.f + __builtin_amdgcn_exp2f(-1.4426950408889634f * x)); }
; __device__ __forceinline__ void gdn_chain(LAS unsigned char* lds, const GdnP& P, const float* out_norm, int bh, const int tid) {
;     ...
;         { const int t = tid >> 3, c16 = tid & 7;
;           bf16_t* op = P.proj + (size_t)(row0 + t) * NIN + C_GDN + 2048 + h * 128 + c16 * 16;
;           *(u32x4*)op = *(const LAS u32x4*)(lds + GC_OB + t * 272 + c16 * 32); *(u32x4*)(op + 8) = *(const LAS u32x4*)(lds + GC_OB + t * 272 + c16 * 32 + 16);
;           if (c16 == 0) { const float tot = ((LAS float*)(lds + GC_RED))[t * 2] + ((LAS float*)(lds + GC_RED))[t * 2 + 1]; P.rstdo[(size_t)(row0 + t) * 8 + h] = __builtin_amdgcn_rsqf(tot * (1.f / 128.f) + EPS); } }
; __global__ void __launch_bounds__(NTHREADS, 2) mega(Args a) {
;     ...
;         for (int idx = bx * NTHREADS + tid; idx < TOK * 64; idx += G * NTHREADS) {
;             const int token = idx >> 6, h = (idx >> 3) & 7, c16 = idx & 7;
;             const bf16_t* op = proj + (size_t)token * NIN + C_GDN + 2048 + h * 128 + c16 * 16; bf16_t* zp = proj + (size_t)token * NIN + C_Z + h * 128 + c16 * 16;
;             const u32x4 o0 = *(const u32x4*)op, o1 = *(const u32x4*)(op + 8), z0 = *(const u32x4*)zp, z1 = *(const u32x4*)(zp + 8);
;             const float rstd = rstdo[(size_t)token * 8 + h];
; #pragma unroll
;             for (int hh = 0; hh < 2; ++hh) { const u32x4 ov = hh ? o1 : o0, zv = hh ? z1 : z0;
;                 const f32x4 g0 = *(const f32x4*)(onorm + c16 * 16 + hh * 8), g1 = *(const f32x4*)(onorm + c16 * 16 + hh * 8 + 4);
;                 float r[8];
; #pragma unroll
;                 for (int e = 0; e < 4; ++e) { const float zl = bflo(zv[e]), zh = bfhi(zv[e]); const float gl = (e < 2 ? g0 : g1)[(2 * e) & 3], gh = (e < 2 ? g0 : g1)[(2 * e + 1) & 3];
;                     r[2 * e] = bflo(ov[e]) * rstd * gl * zl * sigmoidf_(zl); r[2 * e + 1] = bfhi(ov[e]) * rstd * gh * zh * sigmoidf_(zh); }
;                 u32x4 o; o.x = pk2(r[0], r[1]); o.y = pk2(r[2], r[3]); o.z = pk2(r[4], r[5]); o.w = pk2(r[6], r[7]);
;                 *(u32x4*)(zp + hh * 8) = o; }
	v_lshl_add_u64 v[84:85], v[84:85], 0, s[0:1]
	v_mov_b32_e32 v131, v115
	v_lshl_add_u64 v[96:97], v[84:85], 0, v[130:131]
	v_lshl_add_u64 v[96:97], v[96:97], 0, s[26:27]
	ds_read_b128 v[84:87], v149 offset:54272
	ds_read_b128 v[92:95], v149 offset:54288
	v_and_b32_e32 v98, 0xfffffff8, v112
	v_add_u32_e32 v98, 0xd000, v98
	ds_read2_b32 v[98:99], v98 offset1:1
	v_lshlrev_b32_e32 v173, 1, v130
	ds_read_b128 v[178:181], v173 offset:53760
	ds_read_b128 v[182:185], v173 offset:53776
	ds_read_b128 v[186:189], v173 offset:53792
	ds_read_b128 v[190:193], v173 offset:53808
	s_waitcnt vmcnt(15) lgkmcnt(0)
	v_add_f32_e32 v98, v98, v99
	v_fmamk_f32 v98, v98, 0x3c000000, v150
	v_rsq_f32_e32 v98, v98
	v_lshlrev_b32_e32 v206, 16, v84
	v_and_b32_e32 v207, 0xffff0000, v84
	v_lshlrev_b32_e32 v208, 16, v85
	v_and_b32_e32 v209, 0xffff0000, v85
	v_lshlrev_b32_e32 v210, 16, v86
	v_and_b32_e32 v211, 0xffff0000, v86
	v_lshlrev_b32_e32 v212, 16, v87
	v_and_b32_e32 v213, 0xffff0000, v87
	v_lshlrev_b32_e32 v214, 16, v92
	v_and_b32_e32 v215, 0xffff0000, v92
	v_lshlrev_b32_e32 v216, 16, v93
	v_and_b32_e32 v217, 0xffff0000, v93
	v_lshlrev_b32_e32 v218, 16, v94
	v_and_b32_e32 v219, 0xffff0000, v94
	v_lshlrev_b32_e32 v240, 16, v95
	v_and_b32_e32 v241, 0xffff0000, v95
	v_lshlrev_b32_e32 v100, 16, v244
	v_and_b32_e32 v101, 0xffff0000, v244
	v_lshlrev_b32_e32 v102, 16, v245
	v_and_b32_e32 v103, 0xffff0000, v245
	v_lshlrev_b32_e32 v104, 16, v246
	v_and_b32_e32 v105, 0xffff0000, v246
	v_lshlrev_b32_e32 v106, 16, v247
	v_and_b32_e32 v107, 0xffff0000, v247
	v_lshlrev_b32_e32 v108, 16, v248
	v_and_b32_e32 v109, 0xffff0000, v248
	v_lshlrev_b32_e32 v110, 16, v249
	v_and_b32_e32 v111, 0xffff0000, v249
	v_lshlrev_b32_e32 v194, 16, v250
	v_and_b32_e32 v195, 0xffff0000, v250
	v_lshlrev_b32_e32 v196, 16, v251
	v_and_b32_e32 v197, 0xffff0000, v251
	v_mul_f32_e32 v198, 0xbfb8aa3b, v100
	v_mul_f32_e32 v199, 0xbfb8aa3b, v101
	v_mul_f32_e32 v200, 0xbfb8aa3b, v102
	v_mul_f32_e32 v201, 0xbfb8aa3b, v103
	v_mul_f32_e32 v202, 0xbfb8aa3b, v104
	v_mul_f32_e32 v203, 0xbfb8aa3b, v105
	v_mul_f32_e32 v230, 0xbfb8aa3b, v106
	v_mul_f32_e32 v231, 0xbfb8aa3b, v107
	v_mul_f32_e32 v232, 0xbfb8aa3b, v108
	v_mul_f32_e32 v233, 0xbfb8aa3b, v109
	v_mul_f32_e32 v234, 0xbfb8aa3b, v110
	v_mul_f32_e32 v235, 0xbfb8aa3b, v111
	v_mul_f32_e32 v236, 0xbfb8aa3b, v194
	v_mul_f32_e32 v237, 0xbfb8aa3b, v195
	v_mul_f32_e32 v84, 0xbfb8aa3b, v196
	v_mul_f32_e32 v85, 0xbfb8aa3b, v197
	v_exp_f32_e32 v198, v198
	v_exp_f32_e32 v199, v199
	v_exp_f32_e32 v200, v200
	v_exp_f32_e32 v201, v201
	v_exp_f32_e32 v202, v202
	v_exp_f32_e32 v203, v203
	v_exp_f32_e32 v230, v230
	v_exp_f32_e32 v231, v231
	v_exp_f32_e32 v232, v232
	v_exp_f32_e32 v233, v233
	v_exp_f32_e32 v234, v234
	v_exp_f32_e32 v235, v235
	v_exp_f32_e32 v236, v236
	v_exp_f32_e32 v237, v237
	v_exp_f32_e32 v84, v84
	v_exp_f32_e32 v85, v85
	v_pk_mul_f32 v[206:207], v[206:207], v[98:99] op_sel_hi:[1,0]
	v_pk_mul_f32 v[208:209], v[208:209], v[98:99] op_sel_hi:[1,0]
	v_pk_mul_f32 v[210:211], v[210:211], v[98:99] op_sel_hi:[1,0]
	v_pk_mul_f32 v[212:213], v[212:213], v[98:99] op_sel_hi:[1,0]
	v_pk_mul_f32 v[214:215], v[214:215], v[98:99] op_sel_hi:[1,0]
	v_pk_mul_f32 v[216:217], v[216:217], v[98:99] op_sel_hi:[1,0]
	v_pk_mul_f32 v[218:219], v[218:219], v[98:99] op_sel_hi:[1,0]
	v_pk_mul_f32 v[240:241], v[240:241], v[98:99] op_sel_hi:[1,0]
	v_add_f32_e32 v198, 1.0, v198
	v_add_f32_e32 v199, 1.0, v199
	v_add_f32_e32 v200, 1.0, v200
	v_add_f32_e32 v201, 1.0, v201
	v_add_f32_e32 v202, 1.0, v202
	v_add_f32_e32 v203, 1.0, v203
	v_add_f32_e32 v230, 1.0, v230
	v_add_f32_e32 v231, 1.0, v231
	v_add_f32_e32 v232, 1.0, v232
	v_add_f32_e32 v233, 1.0, v233
	v_add_f32_e32 v234, 1.0, v234
	v_add_f32_e32 v235, 1.0, v235
	v_add_f32_e32 v236, 1.0, v236
	v_add_f32_e32 v237, 1.0, v237
	v_add_f32_e32 v84, 1.0, v84
	v_add_f32_e32 v85, 1.0, v85
	v_rcp_f32_e32 v198, v198
	v_rcp_f32_e32 v199, v199
	v_rcp_f32_e32 v200, v200
	v_rcp_f32_e32 v201, v201
	v_rcp_f32_e32 v202, v202
	v_rcp_f32_e32 v203, v203
	v_rcp_f32_e32 v230, v230
	v_rcp_f32_e32 v231, v231
	v_rcp_f32_e32 v232, v232
	v_rcp_f32_e32 v233, v233
	v_rcp_f32_e32 v234, v234
	v_rcp_f32_e32 v235, v235
	v_rcp_f32_e32 v236, v236
	v_rcp_f32_e32 v237, v237
	v_rcp_f32_e32 v84, v84
	v_rcp_f32_e32 v85, v85
	v_pk_mul_f32 v[206:207], v[206:207], v[178:179]
	v_pk_mul_f32 v[208:209], v[208:209], v[180:181]
	v_pk_mul_f32 v[210:211], v[210:211], v[182:183]
	v_pk_mul_f32 v[212:213], v[212:213], v[184:185]
	v_pk_mul_f32 v[214:215], v[214:215], v[186:187]
	v_pk_mul_f32 v[216:217], v[216:217], v[188:189]
	v_pk_mul_f32 v[218:219], v[218:219], v[190:191]
	v_pk_mul_f32 v[240:241], v[240:241], v[192:193]
	v_pk_mul_f32 v[206:207], v[206:207], v[100:101]
	v_pk_mul_f32 v[208:209], v[208:209], v[102:103]
	v_pk_mul_f32 v[210:211], v[210:211], v[104:105]
	v_pk_mul_f32 v[212:213], v[212:213], v[106:107]
	v_pk_mul_f32 v[214:215], v[214:215], v[108:109]
	v_pk_mul_f32 v[216:217], v[216:217], v[110:111]
	v_pk_mul_f32 v[218:219], v[218:219], v[194:195]
	v_pk_mul_f32 v[240:241], v[240:241], v[196:197]
	v_pk_mul_f32 v[206:207], v[206:207], v[198:199]
	v_pk_mul_f32 v[208:209], v[208:209], v[200:201]
	v_pk_mul_f32 v[210:211], v[210:211], v[202:203]
	v_pk_mul_f32 v[212:213], v[212:213], v[230:231]
	v_pk_mul_f32 v[214:215], v[214:215], v[232:233]
	v_pk_mul_f32 v[216:217], v[216:217], v[234:235]
	v_pk_mul_f32 v[218:219], v[218:219], v[236:237]
	v_pk_mul_f32 v[240:241], v[240:241], v[84:85]
	v_cvt_pk_bf16_f32 v100, v206, v207
	v_cvt_pk_bf16_f32 v101, v208, v209
	v_cvt_pk_bf16_f32 v102, v210, v211
	v_cvt_pk_bf16_f32 v103, v212, v213
	v_cvt_pk_bf16_f32 v104, v214, v215
	v_cvt_pk_bf16_f32 v105, v216, v217
	v_cvt_pk_bf16_f32 v106, v218, v219
	v_cvt_pk_bf16_f32 v107, v240, v241
	global_store_dwordx4 v[96:97], v[100:103], off offset:2048
	global_store_dwordx4 v[96:97], v[104:107], off offset:2064
	v_lshl_add_u64 v[220:221], v[220:221], 0, s[78:79]
	global_load_dwordx4 v[244:247], v[220:221], off offset:2048
	global_load_dwordx4 v[248:251], v[220:221], off offset:2064
	s_mov_b64 s[30:31], exec
	s_branch .LBB0_1125
